# xattn PV loop pipelined + mixnorm pass folded into out-proj GEMM (mid-K-loop acc rescale by rs_a/rs_b, epilogue rs_b)
# speedup vs baseline: 1.0194x; 1.0141x over previous
.LBB0_1702:
	v_readlane_b32 s4, v244, 47
	s_cmp_lt_i32 s4, 7
	s_cselect_b64 s[2:3], -1, 0
	s_and_b64 s[2:3], s[2:3], s[0:1]
	s_andn2_b64 vcc, exec, s[2:3]
	v_readlane_b32 s5, v244, 48
	v_readlane_b32 s6, v244, 49
	v_readlane_b32 s7, v244, 50
	s_cbranch_vccnz .LBB0_1715
	s_cmpk_gt_i32 s89, 0x2fff
	s_branch .LBB0_1712

.LBB0_1781:
	s_cmp_eq_u32 s56, 6
	s_cbranch_scc0 .Lp7_skip_rescale
	v_readlane_b32 s98, v244, 6
	v_readlane_b32 s99, v244, 7
	v_lshl_add_u32 v232, s28, 8, v145
	s_add_u32 s98, s98, 0x1fb20000
	s_addc_u32 s99, s99, 0
	v_lshlrev_b32_e32 v232, 2, v232
	s_add_u32 s100, s98, 0x30000
	s_addc_u32 s101, s99, 0
	global_load_dword v233, v232, s[98:99] offset:0
	global_load_dword v234, v232, s[98:99] offset:64
	global_load_dword v235, v232, s[98:99] offset:128
	global_load_dword v236, v232, s[98:99] offset:192
	global_load_dword v237, v232, s[98:99] offset:512
	global_load_dword v238, v232, s[98:99] offset:576
	global_load_dword v239, v232, s[98:99] offset:640
	global_load_dword v240, v232, s[98:99] offset:704
	global_load_dword v241, v232, s[100:101] offset:0
	global_load_dword v242, v232, s[100:101] offset:64
	global_load_dword v243, v232, s[100:101] offset:128
	global_load_dword v245, v232, s[100:101] offset:192
	global_load_dword v246, v232, s[100:101] offset:512
	global_load_dword v247, v232, s[100:101] offset:576
	global_load_dword v248, v232, s[100:101] offset:640
	global_load_dword v249, v232, s[100:101] offset:704
	v_mov_b32_e32 v250, 0x358637bd
	s_waitcnt vmcnt(0)
	v_fmamk_f32 v233, v233, 0x3b000000, v250
	v_fmamk_f32 v234, v234, 0x3b000000, v250
	v_fmamk_f32 v235, v235, 0x3b000000, v250
	v_fmamk_f32 v236, v236, 0x3b000000, v250
	v_fmamk_f32 v237, v237, 0x3b000000, v250
	v_fmamk_f32 v238, v238, 0x3b000000, v250
	v_fmamk_f32 v239, v239, 0x3b000000, v250
	v_fmamk_f32 v240, v240, 0x3b000000, v250
	v_fmamk_f32 v241, v241, 0x3b000000, v250
	v_fmamk_f32 v242, v242, 0x3b000000, v250
	v_fmamk_f32 v243, v243, 0x3b000000, v250
	v_fmamk_f32 v245, v245, 0x3b000000, v250
	v_fmamk_f32 v246, v246, 0x3b000000, v250
	v_fmamk_f32 v247, v247, 0x3b000000, v250
	v_fmamk_f32 v248, v248, 0x3b000000, v250
	v_fmamk_f32 v249, v249, 0x3b000000, v250
	v_rcp_f32_e32 v233, v233
	v_rcp_f32_e32 v234, v234
	v_rcp_f32_e32 v235, v235
	v_rcp_f32_e32 v236, v236
	v_rcp_f32_e32 v237, v237
	v_rcp_f32_e32 v238, v238
	v_rcp_f32_e32 v239, v239
	v_rcp_f32_e32 v240, v240
	s_nop 0
	v_mul_f32_e32 v233, v233, v241
	v_mul_f32_e32 v234, v234, v242
	v_mul_f32_e32 v235, v235, v243
	v_mul_f32_e32 v236, v236, v245
	v_mul_f32_e32 v237, v237, v246
	v_mul_f32_e32 v238, v238, v247
	v_mul_f32_e32 v239, v239, v248
	v_mul_f32_e32 v240, v240, v249
	v_sqrt_f32_e32 v233, v233
	v_sqrt_f32_e32 v234, v234
	v_sqrt_f32_e32 v235, v235
	v_sqrt_f32_e32 v236, v236
	v_sqrt_f32_e32 v237, v237
	v_sqrt_f32_e32 v238, v238
	v_sqrt_f32_e32 v239, v239
	v_sqrt_f32_e32 v240, v240
	v_rsq_f32_e32 v241, v241
	v_rsq_f32_e32 v242, v242
	v_rsq_f32_e32 v243, v243
	v_rsq_f32_e32 v245, v245
	v_rsq_f32_e32 v246, v246
	v_rsq_f32_e32 v247, v247
	v_rsq_f32_e32 v248, v248
	v_rsq_f32_e32 v249, v249
	s_nop 0
	v_mul_f32_e32 v112, v112, v233
	v_mul_f32_e32 v113, v113, v233
	v_mul_f32_e32 v114, v114, v233
	v_mul_f32_e32 v115, v115, v233
	v_mul_f32_e32 v116, v116, v233
	v_mul_f32_e32 v117, v117, v233
	v_mul_f32_e32 v118, v118, v233
	v_mul_f32_e32 v119, v119, v233
	v_mul_f32_e32 v120, v120, v233
	v_mul_f32_e32 v121, v121, v233
	v_mul_f32_e32 v122, v122, v233
	v_mul_f32_e32 v123, v123, v233
	v_mul_f32_e32 v124, v124, v233
	v_mul_f32_e32 v125, v125, v233
	v_mul_f32_e32 v126, v126, v233
	v_mul_f32_e32 v127, v127, v233
	v_mul_f32_e32 v96, v96, v234
	v_mul_f32_e32 v97, v97, v234
	v_mul_f32_e32 v98, v98, v234
	v_mul_f32_e32 v99, v99, v234
	v_mul_f32_e32 v100, v100, v234
	v_mul_f32_e32 v101, v101, v234
	v_mul_f32_e32 v102, v102, v234
	v_mul_f32_e32 v103, v103, v234
	v_mul_f32_e32 v104, v104, v234
	v_mul_f32_e32 v105, v105, v234
	v_mul_f32_e32 v106, v106, v234
	v_mul_f32_e32 v107, v107, v234
	v_mul_f32_e32 v108, v108, v234
	v_mul_f32_e32 v109, v109, v234
	v_mul_f32_e32 v110, v110, v234
	v_mul_f32_e32 v111, v111, v234
	v_mul_f32_e32 v80, v80, v235
	v_mul_f32_e32 v81, v81, v235
	v_mul_f32_e32 v82, v82, v235
	v_mul_f32_e32 v83, v83, v235
	v_mul_f32_e32 v84, v84, v235
	v_mul_f32_e32 v85, v85, v235
	v_mul_f32_e32 v86, v86, v235
	v_mul_f32_e32 v87, v87, v235
	v_mul_f32_e32 v88, v88, v235
	v_mul_f32_e32 v89, v89, v235
	v_mul_f32_e32 v90, v90, v235
	v_mul_f32_e32 v91, v91, v235
	v_mul_f32_e32 v92, v92, v235
	v_mul_f32_e32 v93, v93, v235
	v_mul_f32_e32 v94, v94, v235
	v_mul_f32_e32 v95, v95, v235
	v_mul_f32_e32 v64, v64, v236
	v_mul_f32_e32 v65, v65, v236
	v_mul_f32_e32 v66, v66, v236
	v_mul_f32_e32 v67, v67, v236
	v_mul_f32_e32 v68, v68, v236
	v_mul_f32_e32 v69, v69, v236
	v_mul_f32_e32 v70, v70, v236
	v_mul_f32_e32 v71, v71, v236
	v_mul_f32_e32 v72, v72, v236
	v_mul_f32_e32 v73, v73, v236
	v_mul_f32_e32 v74, v74, v236
	v_mul_f32_e32 v75, v75, v236
	v_mul_f32_e32 v76, v76, v236
	v_mul_f32_e32 v77, v77, v236
	v_mul_f32_e32 v78, v78, v236
	v_mul_f32_e32 v79, v79, v236
	v_mul_f32_e32 v48, v48, v237
	v_mul_f32_e32 v49, v49, v237
	v_mul_f32_e32 v50, v50, v237
	v_mul_f32_e32 v51, v51, v237
	v_mul_f32_e32 v52, v52, v237
	v_mul_f32_e32 v53, v53, v237
	v_mul_f32_e32 v54, v54, v237
	v_mul_f32_e32 v55, v55, v237
	v_mul_f32_e32 v56, v56, v237
	v_mul_f32_e32 v57, v57, v237
	v_mul_f32_e32 v58, v58, v237
	v_mul_f32_e32 v59, v59, v237
	v_mul_f32_e32 v60, v60, v237
	v_mul_f32_e32 v61, v61, v237
	v_mul_f32_e32 v62, v62, v237
	v_mul_f32_e32 v63, v63, v237
	v_mul_f32_e32 v32, v32, v238
	v_mul_f32_e32 v33, v33, v238
	v_mul_f32_e32 v34, v34, v238
	v_mul_f32_e32 v35, v35, v238
	v_mul_f32_e32 v36, v36, v238
	v_mul_f32_e32 v37, v37, v238
	v_mul_f32_e32 v38, v38, v238
	v_mul_f32_e32 v39, v39, v238
	v_mul_f32_e32 v40, v40, v238
	v_mul_f32_e32 v41, v41, v238
	v_mul_f32_e32 v42, v42, v238
	v_mul_f32_e32 v43, v43, v238
	v_mul_f32_e32 v44, v44, v238
	v_mul_f32_e32 v45, v45, v238
	v_mul_f32_e32 v46, v46, v238
	v_mul_f32_e32 v47, v47, v238
	v_mul_f32_e32 v16, v16, v239
	v_mul_f32_e32 v17, v17, v239
	v_mul_f32_e32 v18, v18, v239
	v_mul_f32_e32 v19, v19, v239
	v_mul_f32_e32 v20, v20, v239
	v_mul_f32_e32 v21, v21, v239
	v_mul_f32_e32 v22, v22, v239
	v_mul_f32_e32 v23, v23, v239
	v_mul_f32_e32 v24, v24, v239
	v_mul_f32_e32 v25, v25, v239
	v_mul_f32_e32 v26, v26, v239
	v_mul_f32_e32 v27, v27, v239
	v_mul_f32_e32 v28, v28, v239
	v_mul_f32_e32 v29, v29, v239
	v_mul_f32_e32 v30, v30, v239
	v_mul_f32_e32 v31, v31, v239
	v_mul_f32_e32 v0, v0, v240
	v_mul_f32_e32 v1, v1, v240
	v_mul_f32_e32 v2, v2, v240
	v_mul_f32_e32 v3, v3, v240
	v_mul_f32_e32 v4, v4, v240
	v_mul_f32_e32 v5, v5, v240
	v_mul_f32_e32 v6, v6, v240
	v_mul_f32_e32 v7, v7, v240
	v_mul_f32_e32 v8, v8, v240
	v_mul_f32_e32 v9, v9, v240
	v_mul_f32_e32 v10, v10, v240
	v_mul_f32_e32 v11, v11, v240
	v_mul_f32_e32 v12, v12, v240
	v_mul_f32_e32 v13, v13, v240
	v_mul_f32_e32 v14, v14, v240
	v_mul_f32_e32 v15, v15, v240

.LBB0_1784:
	s_lshl_b32 s26, s26, 8
	v_lshl_add_u32 v168, s28, 8, v145
	s_ashr_i32 s27, s26, 31
	s_lshl_b64 s[28:29], s[26:27], 1
	v_ashrrev_i32_e32 v169, 31, v168
	v_lshl_add_u64 v[128:129], v[156:157], 0, s[28:29]
	v_lshlrev_b64 v[172:173], 11, v[168:169]
	v_lshl_add_u64 v[130:131], v[128:129], 0, v[172:173]
	global_load_dwordx4 v[190:193], v[130:131], off
	global_load_dwordx4 v[194:197], v[130:131], off offset:256
	v_lshl_add_u64 v[166:167], v[168:169], 2, s[10:11]
	global_load_dword v198, v[166:167], off
	v_readlane_b32 s56, v244, 0
	v_or_b32_e32 v176, 16, v168
	v_or_b32_e32 v170, 32, v168
	v_readlane_b32 s57, v244, 1
	v_readlane_b32 s58, v244, 2
	v_readlane_b32 s59, v244, 3
	v_readlane_b32 s60, v244, 4
	v_readlane_b32 s61, v244, 5
	v_ashrrev_i32_e32 v177, 31, v176
	v_ashrrev_i32_e32 v171, 31, v170
	v_readlane_b32 s62, v244, 6
	v_readlane_b32 s63, v244, 7
	s_mov_b64 s[56:57], s[60:61]
	v_lshlrev_b64 v[178:179], 11, v[176:177]
	v_lshl_add_u64 v[132:133], v[170:171], 2, s[10:11]
	v_lshlrev_b64 v[134:135], 11, v[170:171]
	s_mov_b64 s[58:59], s[62:63]
	v_lshl_add_u64 v[130:131], v[176:177], 2, s[10:11]
	v_lshl_add_u64 v[128:129], v[128:129], 0, v[178:179]
	global_load_dword v188, v[132:133], off
	v_lshl_add_u64 v[132:133], s[58:59], 0, v[134:135]
	global_load_dword v189, v[130:131], off
	global_load_dwordx4 v[140:143], v[128:129], off
	global_load_dwordx4 v[136:139], v[128:129], off offset:256
	v_lshl_add_u64 v[128:129], v[132:133], 0, s[28:29]
	v_lshl_add_u64 v[174:175], v[128:129], 0, v[154:155]
	global_load_dwordx4 v[132:135], v[174:175], off
	global_load_dwordx4 v[128:131], v[174:175], off offset:256
	v_and_b32_e32 v200, 64, v187
	v_xor_b32_e32 v199, 16, v187
	v_add_u32_e32 v200, 64, v200
	v_cmp_lt_i32_e32 vcc, v199, v200
	v_lshl_add_u64 v[172:173], s[58:59], 0, v[172:173]
	v_mul_f32_e32 v112, v112, v241
	v_mul_f32_e32 v113, v113, v241
	v_mul_f32_e32 v114, v114, v241
	v_mul_f32_e32 v115, v115, v241
	v_mul_f32_e32 v116, v116, v241
	v_mul_f32_e32 v117, v117, v241
	v_mul_f32_e32 v118, v118, v241
	v_mul_f32_e32 v119, v119, v241
	v_mul_f32_e32 v120, v120, v241
	v_mul_f32_e32 v121, v121, v241
	v_mul_f32_e32 v122, v122, v241
	v_mul_f32_e32 v123, v123, v241
	v_mul_f32_e32 v124, v124, v241
	v_mul_f32_e32 v125, v125, v241
	v_mul_f32_e32 v126, v126, v241
	v_mul_f32_e32 v127, v127, v241
	v_mul_f32_e32 v96, v96, v242
	v_mul_f32_e32 v97, v97, v242
	v_mul_f32_e32 v98, v98, v242
	v_mul_f32_e32 v99, v99, v242
	v_mul_f32_e32 v100, v100, v242
	v_mul_f32_e32 v101, v101, v242
	v_mul_f32_e32 v102, v102, v242
	v_mul_f32_e32 v103, v103, v242
	v_mul_f32_e32 v104, v104, v242
	v_mul_f32_e32 v105, v105, v242
	v_mul_f32_e32 v106, v106, v242
	v_mul_f32_e32 v107, v107, v242
	v_mul_f32_e32 v108, v108, v242
	v_mul_f32_e32 v109, v109, v242
	v_mul_f32_e32 v110, v110, v242
	v_mul_f32_e32 v111, v111, v242
	v_mul_f32_e32 v80, v80, v243
	v_mul_f32_e32 v81, v81, v243
	v_mul_f32_e32 v82, v82, v243
	v_mul_f32_e32 v83, v83, v243
	v_mul_f32_e32 v84, v84, v243
	v_mul_f32_e32 v85, v85, v243
	v_mul_f32_e32 v86, v86, v243
	v_mul_f32_e32 v87, v87, v243
	v_mul_f32_e32 v88, v88, v243
	v_mul_f32_e32 v89, v89, v243
	v_mul_f32_e32 v90, v90, v243
	v_mul_f32_e32 v91, v91, v243
	v_mul_f32_e32 v92, v92, v243
	v_mul_f32_e32 v93, v93, v243
	v_mul_f32_e32 v94, v94, v243
	v_mul_f32_e32 v95, v95, v243
	v_mul_f32_e32 v64, v64, v245
	v_mul_f32_e32 v65, v65, v245
	v_mul_f32_e32 v66, v66, v245
	v_mul_f32_e32 v67, v67, v245
	v_mul_f32_e32 v68, v68, v245
	v_mul_f32_e32 v69, v69, v245
	v_mul_f32_e32 v70, v70, v245
	v_mul_f32_e32 v71, v71, v245
	v_mul_f32_e32 v72, v72, v245
	v_mul_f32_e32 v73, v73, v245
	v_mul_f32_e32 v74, v74, v245
	v_mul_f32_e32 v75, v75, v245
	v_mul_f32_e32 v76, v76, v245
	v_mul_f32_e32 v77, v77, v245
	v_mul_f32_e32 v78, v78, v245
	v_mul_f32_e32 v79, v79, v245
	v_mul_f32_e32 v48, v48, v246
	v_mul_f32_e32 v49, v49, v246
	v_mul_f32_e32 v50, v50, v246
	v_mul_f32_e32 v51, v51, v246
	v_mul_f32_e32 v52, v52, v246
	v_mul_f32_e32 v53, v53, v246
	v_mul_f32_e32 v54, v54, v246
	v_mul_f32_e32 v55, v55, v246
	v_mul_f32_e32 v56, v56, v246
	v_mul_f32_e32 v57, v57, v246
	v_mul_f32_e32 v58, v58, v246
	v_mul_f32_e32 v59, v59, v246
	v_mul_f32_e32 v60, v60, v246
	v_mul_f32_e32 v61, v61, v246
	v_mul_f32_e32 v62, v62, v246
	v_mul_f32_e32 v63, v63, v246
	v_mul_f32_e32 v32, v32, v247
	v_mul_f32_e32 v33, v33, v247
	v_mul_f32_e32 v34, v34, v247
	v_mul_f32_e32 v35, v35, v247
	v_mul_f32_e32 v36, v36, v247
	v_mul_f32_e32 v37, v37, v247
	v_mul_f32_e32 v38, v38, v247
	v_mul_f32_e32 v39, v39, v247
	v_mul_f32_e32 v40, v40, v247
	v_mul_f32_e32 v41, v41, v247
	v_mul_f32_e32 v42, v42, v247
	v_mul_f32_e32 v43, v43, v247
	v_mul_f32_e32 v44, v44, v247
	v_mul_f32_e32 v45, v45, v247
	v_mul_f32_e32 v46, v46, v247
	v_mul_f32_e32 v47, v47, v247
	v_mul_f32_e32 v16, v16, v248
	v_mul_f32_e32 v17, v17, v248
	v_mul_f32_e32 v18, v18, v248
	v_mul_f32_e32 v19, v19, v248
	v_mul_f32_e32 v20, v20, v248
	v_mul_f32_e32 v21, v21, v248
	v_mul_f32_e32 v22, v22, v248
	v_mul_f32_e32 v23, v23, v248
	v_mul_f32_e32 v24, v24, v248
	v_mul_f32_e32 v25, v25, v248
	v_mul_f32_e32 v26, v26, v248
	v_mul_f32_e32 v27, v27, v248
	v_mul_f32_e32 v28, v28, v248
	v_mul_f32_e32 v29, v29, v248
	v_mul_f32_e32 v30, v30, v248
	v_mul_f32_e32 v31, v31, v248
	v_mul_f32_e32 v0, v0, v249
	v_mul_f32_e32 v1, v1, v249
	v_mul_f32_e32 v2, v2, v249
	v_mul_f32_e32 v3, v3, v249
	v_mul_f32_e32 v4, v4, v249
	v_mul_f32_e32 v5, v5, v249
	v_mul_f32_e32 v6, v6, v249
	v_mul_f32_e32 v7, v7, v249
	v_mul_f32_e32 v8, v8, v249
	v_mul_f32_e32 v9, v9, v249
	v_mul_f32_e32 v10, v10, v249
	v_mul_f32_e32 v11, v11, v249
	v_mul_f32_e32 v12, v12, v249
	v_mul_f32_e32 v13, v13, v249
	v_mul_f32_e32 v14, v14, v249
	v_mul_f32_e32 v15, v15, v249
	s_waitcnt vmcnt(0)
	v_lshlrev_b32_e32 v201, 16, v190
	v_and_b32_e32 v190, 0xffff0000, v190
	v_lshlrev_b32_e32 v202, 16, v191
	v_and_b32_e32 v191, 0xffff0000, v191
	v_lshlrev_b32_e32 v205, 16, v194
	v_and_b32_e32 v194, 0xffff0000, v194
	v_lshlrev_b32_e32 v206, 16, v195
	v_and_b32_e32 v195, 0xffff0000, v195
	v_lshlrev_b32_e32 v203, 16, v192
	v_and_b32_e32 v192, 0xffff0000, v192
	v_lshlrev_b32_e32 v207, 16, v196
	v_and_b32_e32 v196, 0xffff0000, v196
	v_fma_f32 v125, v198, v190, v125
	v_fmac_f32_e32 v127, v198, v191
	v_fma_f32 v117, v198, v194, v117
	v_fmac_f32_e32 v119, v198, v195
	v_lshlrev_b32_e32 v204, 16, v193
	v_and_b32_e32 v193, 0xffff0000, v193
	v_lshlrev_b32_e32 v208, 16, v197
	v_and_b32_e32 v197, 0xffff0000, v197
	v_fma_f32 v124, v198, v201, v124
	v_fma_f32 v126, v198, v202, v126
	v_fma_f32 v121, v198, v192, v121
	v_fma_f32 v116, v198, v205, v116
	v_fma_f32 v118, v198, v206, v118
	v_fma_f32 v194, v198, v207, v112
	v_fma_f32 v195, v198, v196, v113
	v_cvt_pk_bf16_f32 v190, v124, v125
	v_cvt_pk_bf16_f32 v191, v126, v127
	v_mul_f32_e32 v112, v125, v125
	v_mul_f32_e32 v113, v127, v127
	v_mul_f32_e32 v125, v117, v117
	v_mul_f32_e32 v127, v119, v119
	v_fma_f32 v120, v198, v203, v120
	v_fmac_f32_e32 v123, v198, v193
	v_fmac_f32_e32 v115, v198, v197
	v_cvt_pk_bf16_f32 v192, v120, v121
	v_mul_f32_e32 v121, v121, v121
	v_mul_f32_e32 v196, v195, v195
	v_fmac_f32_e32 v112, v124, v124
	v_fmac_f32_e32 v113, v126, v126
	v_fmac_f32_e32 v125, v116, v116
	v_fmac_f32_e32 v127, v118, v118
	v_fma_f32 v122, v198, v204, v122
	v_fma_f32 v114, v198, v208, v114
	v_cvt_pk_bf16_f32 v193, v122, v123
	v_mul_f32_e32 v123, v123, v123
	v_mul_f32_e32 v197, v115, v115
	v_fmac_f32_e32 v121, v120, v120
	v_fmac_f32_e32 v196, v194, v194
	v_add_f32_e32 v112, v112, v113
	v_add_f32_e32 v113, v125, v127
	v_fmac_f32_e32 v123, v122, v122
	v_fmac_f32_e32 v197, v114, v114
	v_add_f32_e32 v112, v121, v112
	v_add_f32_e32 v113, v196, v113
	v_add_f32_e32 v112, v123, v112
	v_add_f32_e32 v113, v197, v113
	v_add_f32_e32 v122, v112, v113
	v_cndmask_b32_e32 v112, v187, v199, vcc
	v_lshlrev_b32_e32 v124, 2, v112
	ds_bpermute_b32 v123, v124, v122
	v_lshl_add_u64 v[112:113], v[172:173], 0, s[28:29]
	v_lshl_add_u64 v[120:121], v[112:113], 0, v[154:155]
	v_xor_b32_e32 v113, 32, v187
	v_cmp_lt_i32_e32 vcc, v113, v200
	s_waitcnt lgkmcnt(0)
	v_add_f32_e32 v112, v122, v123
	global_store_dwordx4 v[120:121], v[190:193], off
	v_cndmask_b32_e32 v113, v187, v113, vcc
	v_lshlrev_b32_e32 v125, 2, v113
	ds_bpermute_b32 v113, v125, v112
	v_cvt_pk_bf16_f32 v116, v116, v117
	v_cvt_pk_bf16_f32 v117, v118, v119
	v_cvt_pk_bf16_f32 v118, v194, v195
	v_cvt_pk_bf16_f32 v119, v114, v115
	global_store_dwordx4 v[120:121], v[116:119], off offset:256
	s_and_saveexec_b64 s[30:31], s[0:1]
	s_cbranch_execz .LBB0_1786
	v_lshl_add_u64 v[114:115], v[168:169], 2, s[6:7]
	s_waitcnt lgkmcnt(0)
	v_add_f32_e32 v112, v112, v113
	global_atomic_add_f32 v[114:115], v112, off

.LBB0_1952:
	v_lshl_add_u64 v[18:19], v[4:5], 0, s[0:1]
	v_add_co_u32_e32 v10, vcc, 0x19800000, v18
	v_lshl_add_u64 v[14:15], v[2:3], 0, s[0:1]
	s_nop 0
	v_addc_co_u32_e32 v11, vcc, 0, v19, vcc
	v_add_co_u32_e32 v18, vcc, 0x19828000, v18
	v_lshl_add_u64 v[22:23], v[0:1], 0, s[0:1]
	s_nop 0
	v_addc_co_u32_e32 v19, vcc, 0, v19, vcc
	global_load_dwordx4 v[10:13], v[10:11], off
	s_nop 0
	global_load_dwordx4 v[14:17], v[14:15], off
	s_nop 0
	global_load_dwordx4 v[18:21], v[18:19], off
	s_nop 0
	global_load_dwordx4 v[22:25], v[22:23], off
	s_add_u32 s0, s0, 0x50000
	s_addc_u32 s1, s1, 0
	s_cmp_eq_u32 s0, 0x140000
	s_waitcnt vmcnt(3)
	ds_write_b128 v6, v[10:13]
	s_waitcnt vmcnt(2)
	ds_write_b128 v7, v[14:17]
	v_add_u32_e32 v7, 0x8400, v7
	s_waitcnt vmcnt(1)
	ds_write_b128 v6, v[18:21] offset:16896
	s_waitcnt vmcnt(0)
	ds_write_b128 v8, v[22:25]
	v_add_u32_e32 v8, 0x8400, v8
	v_add_u32_e32 v6, 0x8400, v6
	s_cbranch_scc0 .LBB0_1952
	v_add_f32_e32 v21, 0, v142
	v_add_f32_e32 v21, v143, v21
	v_add_f32_e32 v21, v144, v21
	v_add_f32_e32 v21, v145, v21
	v_add_f32_e32 v21, v21, v40
	v_add_f32_e32 v21, v41, v21
	v_add_f32_e32 v21, v42, v21
	v_add_f32_e32 v21, v43, v21
	v_add_f32_e32 v21, v21, v36
	v_add_f32_e32 v21, v37, v21
	v_add_f32_e32 v21, v38, v21
	v_add_f32_e32 v21, v39, v21
	v_add_f32_e32 v21, v21, v32
	v_add_f32_e32 v21, v33, v21
	v_add_f32_e32 v21, v34, v21
	v_add_f32_e32 v21, v35, v21
	v_add_f32_e32 v21, v21, v44
	v_add_f32_e32 v21, v45, v21
	v_add_f32_e32 v21, v46, v21
	v_add_f32_e32 v21, v47, v21
	v_add_f32_e32 v21, v21, v48
	v_add_f32_e32 v21, v49, v21
	v_add_f32_e32 v21, v50, v21
	v_add_f32_e32 v21, v51, v21
	v_add_f32_e32 v21, v21, v146
	v_add_f32_e32 v21, v147, v21
	v_add_f32_e32 v21, v148, v21
	v_add_f32_e32 v21, v149, v21
	v_add_f32_e32 v21, v21, v150
	v_add_f32_e32 v21, v151, v21
	v_add_f32_e32 v21, v152, v21
	v_add_f32_e32 v21, v153, v21
	v_add_f32_e32 v21, v21, v154
	v_add_f32_e32 v21, v155, v21
	v_add_f32_e32 v21, v156, v21
	v_add_f32_e32 v21, v157, v21
	v_add_f32_e32 v21, v21, v159
	v_add_f32_e32 v21, v161, v21
	v_add_f32_e32 v21, v163, v21
	v_add_f32_e32 v21, v165, v21
	v_add_f32_e32 v21, v21, v166
	v_add_f32_e32 v21, v168, v21
	v_add_f32_e32 v21, v158, v21
	v_add_f32_e32 v21, v160, v21
	v_add_f32_e32 v21, v21, v162
	v_add_f32_e32 v21, v164, v21
	v_add_f32_e32 v21, v167, v21
	v_add_f32_e32 v21, v169, v21
	v_add_f32_e32 v21, v21, v170
	v_add_f32_e32 v21, v171, v21
	v_add_f32_e32 v21, v172, v21
	v_add_f32_e32 v21, v173, v21
	v_add_f32_e32 v21, v21, v26
	v_add_f32_e32 v21, v27, v21
	v_add_f32_e32 v21, v174, v21
	v_add_f32_e32 v21, v28, v21
	v_add_f32_e32 v21, v21, v29
	v_add_f32_e32 v21, v31, v21
	v_add_f32_e32 v21, v30, v21
	v_add_f32_e32 v21, v175, v21
	v_add_f32_e32 v21, v21, v176
	v_add_f32_e32 v21, v177, v21
	v_add_f32_e32 v21, v178, v21
	v_add_f32_e32 v25, v74, v21
	v_cvt_pk_bf16_f32 v6, v32, v33
	ds_bpermute_b32 v32, v80, v25
	v_cvt_pk_bf16_f32 v7, v34, v35
	v_cvt_pk_bf16_f32 v4, v36, v37
	s_waitcnt lgkmcnt(0)
	v_cvt_pk_bf16_f32 v0, v142, v143
	s_waitcnt lgkmcnt(0)
	v_add_f32_e32 v32, v25, v32
	ds_bpermute_b32 v33, v81, v32
	v_cvt_pk_bf16_f32 v1, v144, v145
	v_cvt_pk_bf16_f32 v2, v40, v41
	v_cvt_pk_bf16_f32 v3, v42, v43
	v_cvt_pk_bf16_f32 v5, v38, v39
	s_waitcnt lgkmcnt(0)
	v_add_f32_e32 v32, v32, v33
	v_div_scale_f32 v33, s[0:1], v32, v32, 1.0
	v_rcp_f32_e32 v34, v33
	v_cvt_pk_bf16_f32 v8, v44, v45
	v_cvt_pk_bf16_f32 v9, v46, v47
	v_cvt_pk_bf16_f32 v10, v48, v49
	v_fma_f32 v35, -v33, v34, 1.0
	v_fmac_f32_e32 v34, v35, v34
	v_div_scale_f32 v35, vcc, 1.0, v32, 1.0
	v_mul_f32_e32 v36, v35, v34
	v_fma_f32 v37, -v33, v36, v35
	v_fmac_f32_e32 v36, v37, v34
	v_fma_f32 v33, -v33, v36, v35
	v_div_fmas_f32 v33, v33, v34, v36
	v_div_fixup_f32 v32, v33, v32, 1.0
	v_lshl_add_u64 v[34:35], v[72:73], 0, s[10:11]
	v_cvt_pk_bf16_f32 v11, v50, v51
	v_cvt_pk_bf16_f32 v12, v146, v147
	v_cvt_pk_bf16_f32 v13, v148, v149
	v_cvt_pk_bf16_f32 v14, v150, v151
	v_cvt_pk_bf16_f32 v15, v152, v153
	v_cvt_pk_bf16_f32 v16, v154, v155
	v_cvt_pk_bf16_f32 v17, v156, v157
	v_cvt_pk_bf16_f32 v18, v159, v161
	v_cvt_pk_bf16_f32 v19, v163, v165
	v_cvt_pk_bf16_f32 v20, v166, v168
	v_cvt_pk_bf16_f32 v21, v158, v160
	v_cvt_pk_bf16_f32 v22, v162, v164
	v_cvt_pk_bf16_f32 v23, v167, v169
	v_cvt_pk_bf16_f32 v24, v170, v171
	v_cvt_pk_bf16_f32 v25, v172, v173
	v_cvt_pk_bf16_f32 v26, v26, v27
	v_cvt_pk_bf16_f32 v27, v174, v28
	v_cvt_pk_bf16_f32 v28, v29, v31
	v_cvt_pk_bf16_f32 v29, v30, v175
	v_cvt_pk_bf16_f32 v30, v176, v177
	v_cvt_pk_bf16_f32 v31, v178, v74
	v_mov_b32_e32 v33, v32
	v_lshl_add_u64 v[34:35], v[70:71], 0, v[34:35]
	s_mov_b32 s0, 0
	s_barrier
	v_add_u32_e32 v48, s0, v135
	v_add_u32_e32 v49, 0x4200, v135
	ds_read_b64 v[142:143], v48 offset:0
	ds_read_b64 v[144:145], v48 offset:32
	ds_read_b64 v[146:147], v48 offset:8448
	ds_read_b64 v[148:149], v48 offset:8480
	ds_read_b64 v[150:151], v48 offset:64
	ds_read_b64 v[152:153], v48 offset:96
	ds_read_b64 v[154:155], v48 offset:8512
	ds_read_b64 v[156:157], v48 offset:8544
	ds_read_b64 v[158:159], v48 offset:128
	ds_read_b64 v[160:161], v48 offset:160
	ds_read_b64 v[162:163], v48 offset:8576
	ds_read_b64 v[164:165], v48 offset:8608

	.amdhsa_kernel _Z9hymba_fwd4Args
		.amdhsa_group_segment_fixed_size 0
		.amdhsa_private_segment_fixed_size 0
		.amdhsa_kernarg_size 496
		.amdhsa_user_sgpr_count 2
		.amdhsa_user_sgpr_dispatch_ptr 0
		.amdhsa_user_sgpr_queue_ptr 0
		.amdhsa_user_sgpr_kernarg_segment_ptr 1
		.amdhsa_user_sgpr_dispatch_id 0
		.amdhsa_user_sgpr_kernarg_preload_length 0
		.amdhsa_user_sgpr_kernarg_preload_offset 0
		.amdhsa_user_sgpr_private_segment_size 0
		.amdhsa_uses_dynamic_stack 0
		.amdhsa_enable_private_segment 0
		.amdhsa_system_sgpr_workgroup_id_x 1
		.amdhsa_system_sgpr_workgroup_id_y 0
		.amdhsa_system_sgpr_workgroup_id_z 0
		.amdhsa_system_sgpr_workgroup_info 0
		.amdhsa_system_vgpr_workitem_id 2
		.amdhsa_next_free_vgpr 256
		.amdhsa_next_free_sgpr 102
		.amdhsa_accum_offset 256
		.amdhsa_reserve_vcc 1
		.amdhsa_float_round_mode_32 0
		.amdhsa_float_round_mode_16_64 0
		.amdhsa_float_denorm_mode_32 3
		.amdhsa_float_denorm_mode_16_64 3
		.amdhsa_dx10_clamp 1
		.amdhsa_ieee_mode 1
		.amdhsa_fp16_overflow 0
		.amdhsa_tg_split 0
		.amdhsa_exception_fp_ieee_invalid_op 0
		.amdhsa_exception_fp_denorm_src 0
		.amdhsa_exception_fp_ieee_div_zero 0
		.amdhsa_exception_fp_ieee_overflow 0
		.amdhsa_exception_fp_ieee_underflow 0
		.amdhsa_exception_fp_ieee_inexact 0
		.amdhsa_exception_int_div_zero 0
	.end_amdhsa_kernel

amdhsa.kernels:
  - .agpr_count:     0
    .args:
      - .offset:         0
        .size:           240
        .value_kind:     by_value
      - .offset:         240
        .size:           4
        .value_kind:     hidden_block_count_x
      - .offset:         244
        .size:           4
        .value_kind:     hidden_block_count_y
      - .offset:         248
        .size:           4
        .value_kind:     hidden_block_count_z
      - .offset:         252
        .size:           2
        .value_kind:     hidden_group_size_x
      - .offset:         254
        .size:           2
        .value_kind:     hidden_group_size_y
      - .offset:         256
        .size:           2
        .value_kind:     hidden_group_size_z
      - .offset:         258
        .size:           2
        .value_kind:     hidden_remainder_x
      - .offset:         260
        .size:           2
        .value_kind:     hidden_remainder_y
      - .offset:         262
        .size:           2
        .value_kind:     hidden_remainder_z
      - .offset:         280
        .size:           8
        .value_kind:     hidden_global_offset_x
      - .offset:         288
        .size:           8
        .value_kind:     hidden_global_offset_y
      - .offset:         296
        .size:           8
        .value_kind:     hidden_global_offset_z
      - .offset:         304
        .size:           2
        .value_kind:     hidden_grid_dims
      - .offset:         328
        .size:           8
        .value_kind:     hidden_multigrid_sync_arg
      - .offset:         360
        .size:           4
        .value_kind:     hidden_dynamic_lds_size
    .group_segment_fixed_size: 0
    .kernarg_segment_align: 8
    .kernarg_segment_size: 496
    .language:       OpenCL C
    .language_version:
      - 2
      - 0
    .max_flat_workgroup_size: 512
    .name:           _Z9hymba_fwd4Args
    .private_segment_fixed_size: 0
    .sgpr_count:     108
    .sgpr_spill_count: 264
    .symbol:         _Z9hymba_fwd4Args.kd
    .uniform_work_group_size: 1
    .uses_dynamic_stack: false
    .vgpr_count:     256
    .vgpr_spill_count: 0
    .wavefront_size: 64
